# FFN: A(1,1) stage of next tile issued before the epilogue stores; first K-step waits no longer drain the tile stores (FFN,Z,RES)
# speedup vs baseline: 1.0089x; 1.0033x over previous
; #define PG8_STAGE(bufoff, gbase, voff) do { _Pragma("unroll") for (int _i = 0; _i < 2; ++_i) \
;         __builtin_amdgcn_global_load_lds((const unsigned*)((const char*)(gbase) + (voff)[_i]), (LAS unsigned*)(lds + (bufoff) + ldsw + _i * 8192), 16, 0, 0); } while (0)
; #define PG8_LDA(dst, b, h) do { _Pragma("unroll") for (int m = 0; m < 4; ++m) _Pragma("unroll") for (int k = 0; k < 2; ++k) dst[m][k] = *(const LAS bf16x8*)(lds + PG8_SA(b, h) + aoff + m * 2048 + k * 1024); } while (0)
; #define PG8_LDB(dst, b, h) do { _Pragma("unroll") for (int n = 0; n < 2; ++n) _Pragma("unroll") for (int k = 0; k < 2; ++k) dst[n][k] = *(const LAS bf16x8*)(lds + PG8_SB(b, h) + boff + n * 2048 + k * 1024); } while (0)
; #define PG8_SCHED __builtin_amdgcn_sched_barrier(0)
; template <class Epi>
; __device__ __forceinline__ void gemm_phase(LAS unsigned char* lds, const Gemm g, const StaticOrder& S, const Epi& E, const int tid) {
;     ...
;         for (int t = 0; t < nt; t += 2) {
;             const bool last = (t == nt - 2);
;             const char* a1 = cA + (size_t)(t + 1) * kstep;
;             const char* a2 = last ? nA : cA + (size_t)(t + 2) * kstep; const char* b2 = last ? nB : cB + (size_t)(t + 2) * kstep;
;             const char* a3 = a2 + kstep; const char* b3 = b2 + kstep;
;             PG8_LDB(B0, 0, 0); PG8_LDB(B1, 0, 1); PG8_SCHED; PG8_LDA(At, 0, 0); PG8_STAGE(PG8_SA(1, 1), a1 + hstepA, voffA);
.LBB0_650:
	v_mov_b32_e32 v113, 0
	s_andn2_b64 vcc, exec, s[24:25]
	s_cbranch_vccnz .LBB0_653
	s_add_u32 s21, s8, 0x100
	s_addc_u32 s42, s9, 0
	s_add_u32 s6, s10, 0x80
	s_addc_u32 s7, s11, 0
	s_mov_b32 s8, 0
	s_add_i32 s10, s8, 2
	s_add_u32 s11, s6, 0x80
	s_addc_u32 s9, s7, 0
	s_add_i32 s43, 0, 0x10000
	s_cmp_eq_u32 s67, s8
	s_cselect_b32 s9, s39, s9
	s_cselect_b32 s8, s38, s11
	v_add_u32_e32 v0, s43, v204
	s_cselect_b32 s45, s41, s42
	s_cselect_b32 s44, s40, s21
	s_add_i32 s11, 0, 0x14000
	ds_read_b128 v[130:133], v0
	ds_read_b128 v[134:137], v0 offset:1024
	ds_read_b128 v[138:141], v0 offset:2048
	ds_read_b128 v[142:145], v0 offset:3072
	v_add_u32_e32 v0, s11, v204
	ds_read_b128 v[146:149], v0
	ds_read_b128 v[150:153], v0 offset:1024
	ds_read_b128 v[154:157], v0 offset:2048
	ds_read_b128 v[158:161], v0 offset:3072
	ds_read_b128 v[162:165], v205
	ds_read_b128 v[166:169], v205 offset:1024
	ds_read_b128 v[170:173], v205 offset:2048
	ds_read_b128 v[174:177], v205 offset:3072
	ds_read_b128 v[192:195], v205 offset:4096
	ds_read_b128 v[206:209], v205 offset:5120
	ds_read_b128 v[210:213], v205 offset:6144
	ds_read_b128 v[214:217], v205 offset:7168
	s_cmp_lg_u32 s73, 1
	s_cbranch_scc1 .Lkl652_nofa
	v_lshl_add_u64 v[178:179], s[6:7], 0, v[190:191]
	s_add_i32 m0, s54, 0xc000
	s_nop 0
	global_load_lds_dwordx4 v[178:179], off
	v_lshl_add_u64 v[178:179], s[6:7], 0, v[188:189]
	s_add_i32 m0, s54, 0xe000
	s_nop 0
	global_load_lds_dwordx4 v[178:179], off
.Lkl652_nofa:
	s_waitcnt vmcnt(10)
	s_waitcnt lgkmcnt(0)
	s_barrier
	s_setprio 1
	s_waitcnt lgkmcnt(0)
	v_mfma_f32_16x16x32_bf16 v[110:113], v[130:133], v[162:165], 0
	v_mfma_f32_16x16x32_bf16 v[106:109], v[138:141], v[162:165], 0
	v_mfma_f32_16x16x32_bf16 v[94:97], v[130:133], v[170:173], 0
	v_mfma_f32_16x16x32_bf16 v[90:93], v[138:141], v[170:173], 0
	v_mfma_f32_16x16x32_bf16 v[114:117], v[130:133], v[192:195], 0
	v_mfma_f32_16x16x32_bf16 v[62:65], v[138:141], v[192:195], 0
	v_mfma_f32_16x16x32_bf16 v[126:129], v[130:133], v[210:213], 0
	v_mfma_f32_16x16x32_bf16 v[70:73], v[138:141], v[210:213], 0
	v_mfma_f32_16x16x32_bf16 v[110:113], v[134:137], v[166:169], v[110:113]
	v_mfma_f32_16x16x32_bf16 v[106:109], v[142:145], v[166:169], v[106:109]
	v_mfma_f32_16x16x32_bf16 v[94:97], v[134:137], v[174:177], v[94:97]
	v_mfma_f32_16x16x32_bf16 v[90:93], v[142:145], v[174:177], v[90:93]
	v_mfma_f32_16x16x32_bf16 v[114:117], v[134:137], v[206:209], v[114:117]
	v_mfma_f32_16x16x32_bf16 v[62:65], v[142:145], v[206:209], v[62:65]
	v_mfma_f32_16x16x32_bf16 v[126:129], v[134:137], v[214:217], v[126:129]
	v_mfma_f32_16x16x32_bf16 v[70:73], v[142:145], v[214:217], v[70:73]
	s_setprio 0
	s_setprio 1
	v_mfma_f32_16x16x32_bf16 v[102:105], v[146:149], v[162:165], 0
	v_mfma_f32_16x16x32_bf16 v[98:101], v[154:157], v[162:165], 0
	v_mfma_f32_16x16x32_bf16 v[86:89], v[146:149], v[170:173], 0
	v_mfma_f32_16x16x32_bf16 v[82:85], v[154:157], v[170:173], 0
	v_mfma_f32_16x16x32_bf16 v[118:121], v[146:149], v[192:195], 0
	v_mfma_f32_16x16x32_bf16 v[58:61], v[154:157], v[192:195], 0
	v_mfma_f32_16x16x32_bf16 v[122:125], v[146:149], v[210:213], 0
	v_mfma_f32_16x16x32_bf16 v[66:69], v[154:157], v[210:213], 0
	v_mfma_f32_16x16x32_bf16 v[102:105], v[150:153], v[166:169], v[102:105]
	v_mfma_f32_16x16x32_bf16 v[98:101], v[158:161], v[166:169], v[98:101]
	v_mfma_f32_16x16x32_bf16 v[86:89], v[150:153], v[174:177], v[86:89]
	v_mfma_f32_16x16x32_bf16 v[82:85], v[158:161], v[174:177], v[82:85]
	v_mfma_f32_16x16x32_bf16 v[118:121], v[150:153], v[206:209], v[118:121]
	v_mfma_f32_16x16x32_bf16 v[58:61], v[158:161], v[206:209], v[58:61]
	v_mfma_f32_16x16x32_bf16 v[122:125], v[150:153], v[214:217], v[122:125]
	v_mfma_f32_16x16x32_bf16 v[66:69], v[158:161], v[214:217], v[66:69]
	s_setprio 0
	s_barrier
	s_add_i32 s43, s43, s53
	v_lshl_add_u64 v[178:179], s[44:45], 0, v[182:183]
	s_mov_b32 m0, s43
	ds_read_b128 v[162:165], v205 offset:16384
	ds_read_b128 v[166:169], v205 offset:17408
	ds_read_b128 v[170:173], v205 offset:18432
	ds_read_b128 v[174:177], v205 offset:19456
	ds_read_b128 v[192:195], v205 offset:20480
	ds_read_b128 v[206:209], v205 offset:21504
	ds_read_b128 v[210:213], v205 offset:22528
	ds_read_b128 v[214:217], v205 offset:23552
	global_load_lds_dwordx4 v[178:179], off
	s_add_i32 m0, s43, 0x2000
	v_lshl_add_u64 v[202:203], s[44:45], 0, v[186:187]
	s_add_u32 s44, s44, s12
	s_addc_u32 s45, s45, s13
	s_add_i32 s11, s11, s53
	global_load_lds_dwordx4 v[202:203], off
	v_lshl_add_u64 v[218:219], s[44:45], 0, v[182:183]
	s_mov_b32 m0, s11
	v_lshl_add_u64 v[220:221], s[44:45], 0, v[186:187]
	global_load_lds_dwordx4 v[218:219], off
	s_add_i32 m0, s11, 0x2000
	v_lshl_add_u64 v[222:223], s[8:9], 0, v[180:181]
	global_load_lds_dwordx4 v[220:221], off
	s_mov_b32 m0, s54
	v_lshl_add_u64 v[224:225], s[8:9], 0, v[184:185]
	global_load_lds_dwordx4 v[222:223], off
	s_mov_b32 m0, s55
	s_nop 0
	global_load_lds_dwordx4 v[224:225], off
	s_cmp_eq_u32 s73, 1
	s_cbranch_scc1 .Lkl652_w1f
	s_waitcnt vmcnt(16)
	s_branch .Lkl652_w1j

; #define PG8_STAGE(bufoff, gbase, voff) do { _Pragma("unroll") for (int _i = 0; _i < 2; ++_i) \
;         __builtin_amdgcn_global_load_lds((const unsigned*)((const char*)(gbase) + (voff)[_i]), (LAS unsigned*)(lds + (bufoff) + ldsw + _i * 8192), 16, 0, 0); } while (0)
; #define PG8_LDA(dst, b, h) do { _Pragma("unroll") for (int m = 0; m < 4; ++m) _Pragma("unroll") for (int k = 0; k < 2; ++k) dst[m][k] = *(const LAS bf16x8*)(lds + PG8_SA(b, h) + aoff + m * 2048 + k * 1024); } while (0)
; #define PG8_LDB(dst, b, h) do { _Pragma("unroll") for (int n = 0; n < 2; ++n) _Pragma("unroll") for (int k = 0; k < 2; ++k) dst[n][k] = *(const LAS bf16x8*)(lds + PG8_SB(b, h) + boff + n * 2048 + k * 1024); } while (0)
; #define PG8_MMA(ai, bj, At, Bt) do { __builtin_amdgcn_s_setprio(1); _Pragma("unroll") for (int m = 0; m < 4; ++m) _Pragma("unroll") for (int n = 0; n < 2; ++n) _Pragma("unroll") for (int k = 0; k < 2; ++k) \
;         acc[ai][bj][m][n] = __builtin_amdgcn_mfma_f32_16x16x32_bf16(Bt[n][k], At[m][k], acc[ai][bj][m][n], 0, 0, 0); __builtin_amdgcn_s_setprio(0); } while (0)
; #define PG8_WAIT_V(n) asm volatile("s_waitcnt vmcnt(" #n ")" ::: "memory")
; #define PG8_WAIT_L(n) asm volatile("s_waitcnt lgkmcnt(" #n ")" ::: "memory")
; #define PG8_BAR __builtin_amdgcn_s_barrier()
; #define PG8_SCHED __builtin_amdgcn_sched_barrier(0)
; template <class Epi>
; __device__ __forceinline__ void gemm_phase(LAS unsigned char* lds, const Gemm g, const StaticOrder& S, const Epi& E, const int tid) {
;     ...
;             PG8_WAIT_V(8); PG8_WAIT_L(0); PG8_BAR; PG8_MMA(0, 0, At, B0); PG8_MMA(0, 1, At, B1); PG8_BAR; PG8_SCHED;
;             PG8_LDA(At, 0, 1); PG8_STAGE(PG8_SB(0, 0), b2, voffB); PG8_STAGE(PG8_SB(0, 1), b2 + hstepB, voffB); PG8_STAGE(PG8_SA(0, 0), a2, voffA);
;             PG8_WAIT_V(8); PG8_WAIT_L(0); PG8_BAR; PG8_MMA(1, 0, At, B0); PG8_MMA(1, 1, At, B1); PG8_BAR; PG8_SCHED;
;             PG8_LDB(B0, 1, 0); PG8_LDB(B1, 1, 1); PG8_SCHED; PG8_LDA(At, 1, 0); PG8_STAGE(PG8_SA(0, 1), a2 + hstepA, voffA);
.Lkl652_w1j:
	s_waitcnt lgkmcnt(0)
	s_barrier
	s_setprio 1
	s_waitcnt lgkmcnt(0)
	v_mfma_f32_16x16x32_bf16 v[46:49], v[130:133], v[162:165], 0
	v_mfma_f32_16x16x32_bf16 v[30:33], v[138:141], v[162:165], 0
	v_mfma_f32_16x16x32_bf16 v[38:41], v[130:133], v[170:173], 0
	v_mfma_f32_16x16x32_bf16 v[18:21], v[138:141], v[170:173], 0
	v_mfma_f32_16x16x32_bf16 v[50:53], v[130:133], v[192:195], 0
	v_mfma_f32_16x16x32_bf16 v[2:5], v[138:141], v[192:195], 0
	v_mfma_f32_16x16x32_bf16 v[74:77], v[130:133], v[210:213], 0
	v_mfma_f32_16x16x32_bf16 v[10:13], v[138:141], v[210:213], 0
	v_mfma_f32_16x16x32_bf16 v[46:49], v[134:137], v[166:169], v[46:49]
	v_mfma_f32_16x16x32_bf16 v[30:33], v[142:145], v[166:169], v[30:33]
	v_mfma_f32_16x16x32_bf16 v[38:41], v[134:137], v[174:177], v[38:41]
	v_mfma_f32_16x16x32_bf16 v[18:21], v[142:145], v[174:177], v[18:21]
	v_mfma_f32_16x16x32_bf16 v[50:53], v[134:137], v[206:209], v[50:53]
	v_mfma_f32_16x16x32_bf16 v[2:5], v[142:145], v[206:209], v[2:5]
	v_mfma_f32_16x16x32_bf16 v[74:77], v[134:137], v[214:217], v[74:77]
	v_mfma_f32_16x16x32_bf16 v[10:13], v[142:145], v[214:217], v[10:13]
	s_setprio 0
	s_setprio 1
	v_mfma_f32_16x16x32_bf16 v[42:45], v[146:149], v[162:165], 0
	v_mfma_f32_16x16x32_bf16 v[34:37], v[154:157], v[162:165], 0
	v_mfma_f32_16x16x32_bf16 v[26:29], v[146:149], v[170:173], 0
	v_mfma_f32_16x16x32_bf16 v[22:25], v[154:157], v[170:173], 0
	v_mfma_f32_16x16x32_bf16 v[54:57], v[146:149], v[192:195], 0
	v_mfma_f32_16x16x32_bf16 v[6:9], v[154:157], v[192:195], 0
	v_mfma_f32_16x16x32_bf16 v[78:81], v[146:149], v[210:213], 0
	v_mfma_f32_16x16x32_bf16 v[14:17], v[154:157], v[210:213], 0
	v_mfma_f32_16x16x32_bf16 v[42:45], v[150:153], v[166:169], v[42:45]
	v_mfma_f32_16x16x32_bf16 v[34:37], v[158:161], v[166:169], v[34:37]
	v_mfma_f32_16x16x32_bf16 v[26:29], v[150:153], v[174:177], v[26:29]
	v_mfma_f32_16x16x32_bf16 v[22:25], v[158:161], v[174:177], v[22:25]
	v_mfma_f32_16x16x32_bf16 v[54:57], v[150:153], v[206:209], v[54:57]
	v_mfma_f32_16x16x32_bf16 v[6:9], v[158:161], v[206:209], v[6:9]
	v_mfma_f32_16x16x32_bf16 v[78:81], v[150:153], v[214:217], v[78:81]
	v_mfma_f32_16x16x32_bf16 v[14:17], v[158:161], v[214:217], v[14:17]
	s_setprio 0
	s_barrier
	s_add_i32 s11, 0, 0x18000
	v_add_u32_e32 v0, s11, v204
	s_add_i32 s43, 0, 0x1c000
	ds_read_b128 v[130:133], v0
	ds_read_b128 v[134:137], v0 offset:1024
	ds_read_b128 v[138:141], v0 offset:2048
	ds_read_b128 v[142:145], v0 offset:3072
	v_add_u32_e32 v0, s43, v204
	ds_read_b128 v[146:149], v0
	ds_read_b128 v[150:153], v0 offset:1024
	ds_read_b128 v[154:157], v0 offset:2048
	ds_read_b128 v[158:161], v0 offset:3072
	s_add_u32 s8, s8, s0
	s_addc_u32 s9, s9, s1
	s_mov_b32 m0, s56
	v_lshl_add_u64 v[226:227], s[8:9], 0, v[180:181]
	ds_read_b128 v[162:165], v205 offset:32768
	ds_read_b128 v[166:169], v205 offset:33792
	ds_read_b128 v[170:173], v205 offset:34816
	ds_read_b128 v[174:177], v205 offset:35840
	ds_read_b128 v[192:195], v205 offset:36864
	ds_read_b128 v[206:209], v205 offset:37888
	ds_read_b128 v[210:213], v205 offset:38912
	ds_read_b128 v[214:217], v205 offset:39936
	global_load_lds_dwordx4 v[226:227], off
	v_lshl_add_u64 v[226:227], s[8:9], 0, v[184:185]
	s_mov_b32 m0, s57
	s_nop 0
	global_load_lds_dwordx4 v[226:227], off
	s_cmp_eq_u32 s73, 1
	s_cbranch_scc1 .Lkl652_w2f
	s_waitcnt vmcnt(16)
	s_branch .Lkl652_w2j

; #define PG8_MMA(ai, bj, At, Bt) do { __builtin_amdgcn_s_setprio(1); _Pragma("unroll") for (int m = 0; m < 4; ++m) _Pragma("unroll") for (int n = 0; n < 2; ++n) _Pragma("unroll") for (int k = 0; k < 2; ++k) \
;         acc[ai][bj][m][n] = __builtin_amdgcn_mfma_f32_16x16x32_bf16(Bt[n][k], At[m][k], acc[ai][bj][m][n], 0, 0, 0); __builtin_amdgcn_s_setprio(0); } while (0)
; #define PG8_WAIT_V(n) asm volatile("s_waitcnt vmcnt(" #n ")" ::: "memory")
; #define PG8_WAIT_L(n) asm volatile("s_waitcnt lgkmcnt(" #n ")" ::: "memory")
; #define PG8_BAR __builtin_amdgcn_s_barrier()
; #define PG8_SCHED __builtin_amdgcn_sched_barrier(0)
; template <class Epi>
; __device__ __forceinline__ void gemm_phase(LAS unsigned char* lds, const Gemm g, const StaticOrder& S, const Epi& E, const int tid) {
;     ...
;             PG8_WAIT_V(8); PG8_WAIT_L(0); PG8_BAR; PG8_MMA(0, 0, At, B0); PG8_MMA(0, 1, At, B1); PG8_BAR; PG8_SCHED;
.Lkl652_w2j:
	s_waitcnt lgkmcnt(0)
	s_barrier
	s_setprio 1
	s_waitcnt lgkmcnt(0)
	v_mfma_f32_16x16x32_bf16 v[110:113], v[130:133], v[162:165], v[110:113]
	v_mfma_f32_16x16x32_bf16 v[106:109], v[138:141], v[162:165], v[106:109]
	v_mfma_f32_16x16x32_bf16 v[94:97], v[130:133], v[170:173], v[94:97]
	v_mfma_f32_16x16x32_bf16 v[90:93], v[138:141], v[170:173], v[90:93]
	v_mfma_f32_16x16x32_bf16 v[114:117], v[130:133], v[192:195], v[114:117]
	v_mfma_f32_16x16x32_bf16 v[62:65], v[138:141], v[192:195], v[62:65]
	v_mfma_f32_16x16x32_bf16 v[126:129], v[130:133], v[210:213], v[126:129]
	v_mfma_f32_16x16x32_bf16 v[70:73], v[138:141], v[210:213], v[70:73]
	v_mfma_f32_16x16x32_bf16 v[110:113], v[134:137], v[166:169], v[110:113]
	v_mfma_f32_16x16x32_bf16 v[106:109], v[142:145], v[166:169], v[106:109]
	v_mfma_f32_16x16x32_bf16 v[94:97], v[134:137], v[174:177], v[94:97]
	v_mfma_f32_16x16x32_bf16 v[90:93], v[142:145], v[174:177], v[90:93]
	v_mfma_f32_16x16x32_bf16 v[114:117], v[134:137], v[206:209], v[114:117]
	v_mfma_f32_16x16x32_bf16 v[62:65], v[142:145], v[206:209], v[62:65]
	v_mfma_f32_16x16x32_bf16 v[126:129], v[134:137], v[214:217], v[126:129]
	v_mfma_f32_16x16x32_bf16 v[70:73], v[142:145], v[214:217], v[70:73]
	s_setprio 0
	s_setprio 1
	v_mfma_f32_16x16x32_bf16 v[102:105], v[146:149], v[162:165], v[102:105]
	v_mfma_f32_16x16x32_bf16 v[98:101], v[154:157], v[162:165], v[98:101]
	v_mfma_f32_16x16x32_bf16 v[86:89], v[146:149], v[170:173], v[86:89]
	v_mfma_f32_16x16x32_bf16 v[82:85], v[154:157], v[170:173], v[82:85]
	v_mfma_f32_16x16x32_bf16 v[118:121], v[146:149], v[192:195], v[118:121]
	v_mfma_f32_16x16x32_bf16 v[58:61], v[154:157], v[192:195], v[58:61]
	v_mfma_f32_16x16x32_bf16 v[122:125], v[146:149], v[210:213], v[122:125]
	v_mfma_f32_16x16x32_bf16 v[66:69], v[154:157], v[210:213], v[66:69]
	v_mfma_f32_16x16x32_bf16 v[102:105], v[150:153], v[166:169], v[102:105]
	v_mfma_f32_16x16x32_bf16 v[98:101], v[158:161], v[166:169], v[98:101]
	v_mfma_f32_16x16x32_bf16 v[86:89], v[150:153], v[174:177], v[86:89]
	v_mfma_f32_16x16x32_bf16 v[82:85], v[158:161], v[174:177], v[82:85]
	v_mfma_f32_16x16x32_bf16 v[118:121], v[150:153], v[206:209], v[118:121]
	v_mfma_f32_16x16x32_bf16 v[58:61], v[158:161], v[206:209], v[58:61]
	v_mfma_f32_16x16x32_bf16 v[122:125], v[150:153], v[214:217], v[122:125]
	v_mfma_f32_16x16x32_bf16 v[66:69], v[158:161], v[214:217], v[66:69]
	s_setprio 0
	s_barrier
	s_branch .Lkl652_sp3

; #define PG8_STAGE(bufoff, gbase, voff) do { _Pragma("unroll") for (int _i = 0; _i < 2; ++_i) \
;         __builtin_amdgcn_global_load_lds((const unsigned*)((const char*)(gbase) + (voff)[_i]), (LAS unsigned*)(lds + (bufoff) + ldsw + _i * 8192), 16, 0, 0); } while (0)
; #define PG8_LDA(dst, b, h) do { _Pragma("unroll") for (int m = 0; m < 4; ++m) _Pragma("unroll") for (int k = 0; k < 2; ++k) dst[m][k] = *(const LAS bf16x8*)(lds + PG8_SA(b, h) + aoff + m * 2048 + k * 1024); } while (0)
; #define PG8_LDB(dst, b, h) do { _Pragma("unroll") for (int n = 0; n < 2; ++n) _Pragma("unroll") for (int k = 0; k < 2; ++k) dst[n][k] = *(const LAS bf16x8*)(lds + PG8_SB(b, h) + boff + n * 2048 + k * 1024); } while (0)
; #define PG8_MMA(ai, bj, At, Bt) do { __builtin_amdgcn_s_setprio(1); _Pragma("unroll") for (int m = 0; m < 4; ++m) _Pragma("unroll") for (int n = 0; n < 2; ++n) _Pragma("unroll") for (int k = 0; k < 2; ++k) \
;         acc[ai][bj][m][n] = __builtin_amdgcn_mfma_f32_16x16x32_bf16(Bt[n][k], At[m][k], acc[ai][bj][m][n], 0, 0, 0); __builtin_amdgcn_s_setprio(0); } while (0)
; #define PG8_WAIT_V(n) asm volatile("s_waitcnt vmcnt(" #n ")" ::: "memory")
; #define PG8_WAIT_L(n) asm volatile("s_waitcnt lgkmcnt(" #n ")" ::: "memory")
; #define PG8_BAR __builtin_amdgcn_s_barrier()
; #define PG8_SCHED __builtin_amdgcn_sched_barrier(0)
; template <class Epi>
; __device__ __forceinline__ void gemm_phase(LAS unsigned char* lds, const Gemm g, const StaticOrder& S, const Epi& E, const int tid) {
;     ...
;             PG8_LDB(B0, 0, 0); PG8_LDB(B1, 0, 1); PG8_SCHED; PG8_LDA(At, 0, 0); PG8_STAGE(PG8_SA(1, 1), a1 + hstepA, voffA);
;     ...
;             PG8_LDA(At, 1, 1); PG8_STAGE(PG8_SB(1, 0), b3, voffB); PG8_STAGE(PG8_SB(1, 1), b3 + hstepB, voffB); PG8_STAGE(PG8_SA(1, 0), a3, voffA);
;             PG8_WAIT_V(8); PG8_WAIT_L(0); PG8_BAR; PG8_MMA(1, 0, At, B0); PG8_MMA(1, 1, At, B1); PG8_BAR; PG8_SCHED;
;         }
;         if (wr == 0) PG8_BAR;
;         if constexpr (Epi::ROWPERM) E(acc, cur, wr, wc, 0, 0, has_next ? nxt.pn : -1); else E(acc, cur, wr, wc, 0, 0);
;         if (!has_next) break;
.Lkl652_sp3:
	s_add_i32 s8, s11, s53
	v_lshl_add_u64 v[178:179], v[178:179], 0, s[80:81]
	s_mov_b32 m0, s8
	ds_read_b128 v[162:165], v205 offset:49152
	ds_read_b128 v[166:169], v205 offset:50176
	ds_read_b128 v[170:173], v205 offset:51200
	ds_read_b128 v[174:177], v205 offset:52224
	ds_read_b128 v[192:195], v205 offset:53248
	ds_read_b128 v[206:209], v205 offset:54272
	ds_read_b128 v[210:213], v205 offset:55296
	ds_read_b128 v[214:217], v205 offset:56320
	global_load_lds_dwordx4 v[178:179], off
	v_lshl_add_u64 v[178:179], v[202:203], 0, s[80:81]
	s_add_i32 m0, s8, 0x2000
	s_add_i32 s8, s43, s53
	global_load_lds_dwordx4 v[178:179], off
	v_lshl_add_u64 v[178:179], v[218:219], 0, s[80:81]
	s_mov_b32 m0, s8
	s_nop 0
	global_load_lds_dwordx4 v[178:179], off
	v_lshl_add_u64 v[178:179], v[220:221], 0, s[80:81]
	s_add_i32 m0, s8, 0x2000
	s_nop 0
	global_load_lds_dwordx4 v[178:179], off
	v_lshl_add_u64 v[178:179], v[222:223], 0, s[80:81]
	s_mov_b32 m0, s62
	s_nop 0
	global_load_lds_dwordx4 v[178:179], off
	v_lshl_add_u64 v[178:179], v[224:225], 0, s[80:81]
	s_mov_b32 m0, s63
	s_nop 0
	global_load_lds_dwordx4 v[178:179], off
	s_waitcnt vmcnt(8)
	s_waitcnt lgkmcnt(0)
	s_barrier
	s_setprio 1
	s_waitcnt lgkmcnt(0)
	v_mfma_f32_16x16x32_bf16 v[46:49], v[130:133], v[162:165], v[46:49]
	v_mfma_f32_16x16x32_bf16 v[30:33], v[138:141], v[162:165], v[30:33]
	v_mfma_f32_16x16x32_bf16 v[38:41], v[130:133], v[170:173], v[38:41]
	v_mfma_f32_16x16x32_bf16 v[18:21], v[138:141], v[170:173], v[18:21]
	v_mfma_f32_16x16x32_bf16 v[50:53], v[130:133], v[192:195], v[50:53]
	v_mfma_f32_16x16x32_bf16 v[2:5], v[138:141], v[192:195], v[2:5]
	v_mfma_f32_16x16x32_bf16 v[74:77], v[130:133], v[210:213], v[74:77]
	v_mfma_f32_16x16x32_bf16 v[10:13], v[138:141], v[210:213], v[10:13]
	v_mfma_f32_16x16x32_bf16 v[46:49], v[134:137], v[166:169], v[46:49]
	v_mfma_f32_16x16x32_bf16 v[30:33], v[142:145], v[166:169], v[30:33]
	v_mfma_f32_16x16x32_bf16 v[38:41], v[134:137], v[174:177], v[38:41]
	v_mfma_f32_16x16x32_bf16 v[18:21], v[142:145], v[174:177], v[18:21]
	v_mfma_f32_16x16x32_bf16 v[50:53], v[134:137], v[206:209], v[50:53]
	v_mfma_f32_16x16x32_bf16 v[2:5], v[142:145], v[206:209], v[2:5]
	v_mfma_f32_16x16x32_bf16 v[74:77], v[134:137], v[214:217], v[74:77]
	v_mfma_f32_16x16x32_bf16 v[10:13], v[142:145], v[214:217], v[10:13]
	s_setprio 0
	s_setprio 1
	v_mfma_f32_16x16x32_bf16 v[42:45], v[146:149], v[162:165], v[42:45]
	v_mfma_f32_16x16x32_bf16 v[34:37], v[154:157], v[162:165], v[34:37]
	v_mfma_f32_16x16x32_bf16 v[26:29], v[146:149], v[170:173], v[26:29]
	v_mfma_f32_16x16x32_bf16 v[22:25], v[154:157], v[170:173], v[22:25]
	v_mfma_f32_16x16x32_bf16 v[54:57], v[146:149], v[192:195], v[54:57]
	v_mfma_f32_16x16x32_bf16 v[6:9], v[154:157], v[192:195], v[6:9]
	v_mfma_f32_16x16x32_bf16 v[78:81], v[146:149], v[210:213], v[78:81]
	v_mfma_f32_16x16x32_bf16 v[14:17], v[154:157], v[210:213], v[14:17]
	v_mfma_f32_16x16x32_bf16 v[42:45], v[150:153], v[166:169], v[42:45]
	v_mfma_f32_16x16x32_bf16 v[34:37], v[158:161], v[166:169], v[34:37]
	v_mfma_f32_16x16x32_bf16 v[26:29], v[150:153], v[174:177], v[26:29]
	v_mfma_f32_16x16x32_bf16 v[22:25], v[158:161], v[174:177], v[22:25]
	v_mfma_f32_16x16x32_bf16 v[54:57], v[150:153], v[206:209], v[54:57]
	v_mfma_f32_16x16x32_bf16 v[6:9], v[158:161], v[206:209], v[6:9]
	v_mfma_f32_16x16x32_bf16 v[78:81], v[150:153], v[214:217], v[78:81]
	v_mfma_f32_16x16x32_bf16 v[14:17], v[158:161], v[214:217], v[14:17]
	s_setprio 0
	s_barrier
	s_add_u32 s21, s21, 0x100
	s_addc_u32 s42, s42, 0
	s_add_u32 s6, s6, 0x100
	s_addc_u32 s7, s7, 0
	s_cmp_ge_i32 s10, s64
	s_mov_b32 s8, s10
	s_cbranch_scc0 .LBB0_652
	s_and_b64 vcc, exec, s[4:5]
	s_cbranch_vccnz .Lkl652_noa
	s_add_u32 s98, s38, 0x80
	s_addc_u32 s99, s39, 0
	v_lshl_add_u64 v[178:179], s[98:99], 0, v[190:191]
	s_add_i32 m0, s54, 0xc000
	s_nop 0
	global_load_lds_dwordx4 v[178:179], off
	v_lshl_add_u64 v[178:179], s[98:99], 0, v[188:189]
	s_add_i32 m0, s54, 0xe000
	s_nop 0
	global_load_lds_dwordx4 v[178:179], off
.Lkl652_noa:
.LBB0_653:
	s_and_b64 vcc, exec, s[26:27]
	s_cbranch_vccz .LBB0_655
	s_barrier

; #define PG8_BAR __builtin_amdgcn_s_barrier()
; template <class Epi>
; __device__ __forceinline__ void gemm_phase(LAS unsigned char* lds, const Gemm g, const StaticOrder& S, const Epi& E, const int tid) {
;     ...
;         if (!has_next) break;
; #pragma unroll
;         for (int a = 0; a < 2; ++a)
; #pragma unroll
;             for (int b = 0; b < 2; ++b)
; #pragma unroll
;                 for (int m = 0; m < 4; ++m)
; #pragma unroll
;                     for (int n = 0; n < 2; ++n) acc[a][b][m][n] = (f32x4){0.f, 0.f, 0.f, 0.f};
;         cur = nxt; cA = nA; cB = nB; ++ui;
;         if (wr == 1) PG8_BAR;
.LBB0_749:
	s_waitcnt vmcnt(8)
	s_or_b64 exec, exec, s[8:9]
	s_and_b64 vcc, exec, s[4:5]
	s_mov_b64 s[4:5], -1
	s_cbranch_vccnz .LBB0_643
	s_andn2_b64 vcc, exec, s[18:19]
	s_cbranch_vccnz .LBB0_642
	s_barrier
	s_branch .LBB0_642
